# attention: static s_setprio 1 for the younger wave half (waves 4-7, hf==1) for the attention phase (lever 4 as in the guide), reset at phase end
# speedup vs baseline: 1.0031x; 1.0010x over previous
; #define LAS __attribute__((address_space(3)))
; __device__ __forceinline__ void attn_phase(const bf16_t* Q, const bf16_t* Kb, const bf16_t* VTa, const float* rpb, bf16_t* Y, LAS unsigned char* lds, int bx, int G, int tid, int wave, int lane) {
;     const int g = wave & 3, hf = wave >> 2;
;     const int fr = lane & 15, fq = lane >> 4;
;     const int cs = (g == 0) ? 0 : ((g == 1) ? 8 : ((g == 2) ? 24 : 32));
;     const int c = 16 * g + fr;
;     const int colstart = min(max(c - 8, 0), 48);
;     const int kc0 = cs + 8 * fq;
;     const int dci0 = kc0 - c + 15;
;     const int wlo = max(colstart - kc0, 0), wwd = max(min(colstart + 16 - kc0, 8) - wlo, 0);
;     LAS unsigned char* KL = lds; LAS unsigned char* VL = lds + 65536; LAS float* rl = (LAS float*)(lds + 131072);
;     const int lr = lane >> 3, lc = lane & 7;
.LBB0_445:
	v_readlane_b32 s12, v254, 57
	v_readlane_b32 s13, v254, 58
	s_add_u32 s18, s0, 0x1fc00000
	v_lshrrev_b32_e32 v39, 4, v220
	v_cndmask_b32_e64 v0, 0, 1, s[12:13]
	v_cmp_ne_u32_e64 s[16:17], 1, v0
	s_addc_u32 s19, s1, 0
	v_and_b32_e32 v219, 15, v218
	v_writelane_b32 v163, s16, 43
	s_andn2_b64 vcc, exec, s[12:13]
	v_and_b32_e32 v43, 7, v218
	v_lshlrev_b32_e32 v40, 4, v39
	v_lshlrev_b32_e32 v38, 2, v39
	v_writelane_b32 v163, s17, 44
	s_cbranch_vccnz .LBB0_470
	v_lshl_or_b32 v47, s20, 4, v219
	v_sub_u32_e64 v0, v47, 8 clamp
	v_min_u32_e32 v2, 48, v0
	v_lshlrev_b32_e32 v0, 3, v39
	v_add_u32_e32 v3, s22, v0
	v_sub_u32_e32 v2, v2, v3
	v_add_u32_e32 v4, 16, v2
	v_min_i32_e32 v4, 8, v4
	v_max_i32_e32 v5, 0, v2
	s_add_u32 s62, s0, 0x17c00000
	v_sub_u32_e32 v2, v4, v5
	s_addc_u32 s63, s1, 0
	v_max_i32_e32 v7, 0, v2
	v_sub_u32_e32 v2, v3, v47
	v_writelane_b32 v163, s46, 47
	s_add_u32 s21, s0, 0x18c00000
	v_add_u32_e32 v46, 0xe8, v2
	v_lshlrev_b32_e32 v2, 1, v220
	v_writelane_b32 v163, s47, 48
	s_addc_u32 s83, s1, 0
	v_and_b32_e32 v3, 24, v2
	s_add_u32 s34, s0, 0x1ac00000
	v_readlane_b32 s12, v163, 39
	v_add_u32_e32 v3, s22, v3
	s_addc_u32 s35, s1, 0
	s_mulk_i32 s12, 0x7440
	v_and_or_b32 v11, v218, 3, v3
	v_bfe_u32 v3, v3, 3, 2
	v_and_b32_e32 v2, 4, v2
	s_add_u32 s16, s78, s12
	s_movk_i32 s12, 0x1d1
	v_mov_b32_e32 v41, v1
	v_bitop3_b32 v6, v3, v39, v2 bitop3:0x36
	s_addc_u32 s17, s79, 0
	v_lshrrev_b32_e32 v4, 2, v220
	v_cmp_gt_i32_e64 s[38:39], s12, v218
	v_lshl_add_u64 v[44:45], s[62:63], 0, v[40:41]
	v_lshlrev_b32_e32 v41, 4, v6
	v_or_b32_e32 v6, 4, v39
	s_lshr_b32 s12, s22, 3
	v_lshrrev_b32_e32 v42, 3, v220
	v_and_b32_e32 v9, 4, v4
	v_bitop3_b32 v2, v3, v6, v2 bitop3:0x36
	v_add_u32_e32 v6, s12, v39
	v_lshrrev_b32_e32 v8, 1, v218
	v_lshlrev_b32_e32 v55, 4, v2
	v_bitop3_b32 v2, v9, v43, s20 bitop3:0x36
	v_bitop3_b32 v6, v6, v8, 7 bitop3:0x78
	v_bitop3_b32 v8, v9, v43, 1 bitop3:0x36
	v_bitop3_b32 v12, v9, v43, 2 bitop3:0x36
	v_or_b32_e32 v56, 24, v42
	v_bitop3_b32 v9, v9, v43, 3 bitop3:0x36
	v_lshlrev_b32_e32 v14, 3, v9
	v_lshrrev_b32_e32 v9, 1, v56
	v_xor_b32_e32 v9, v9, v220
	v_lshlrev_b32_e32 v9, 3, v9
	v_or_b32_e32 v60, 40, v42
	v_and_b32_e32 v16, 56, v9
	v_lshrrev_b32_e32 v9, 1, v60
	v_xor_b32_e32 v9, v9, v220
	v_lshlrev_b32_e32 v9, 3, v9
	v_or_b32_e32 v64, 56, v42
	v_and_b32_e32 v18, 56, v9
	v_lshrrev_b32_e32 v9, 1, v64
	v_xor_b32_e32 v9, v9, v220
	v_lshlrev_b32_e32 v9, 3, v9
	v_lshl_or_b32 v48, s82, 3, v42
	v_and_b32_e32 v20, 56, v9
	v_sub_u32_e32 v9, 0, v5
	v_ashrrev_i32_e32 v49, 31, v48
	v_lshlrev_b32_e32 v3, 7, v219
	s_add_i32 s88, 0, 0x10000
	v_lshlrev_b32_e32 v6, 4, v6
	v_cmp_gt_u32_e64 s[40:41], v7, v9
	v_sub_u32_e32 v9, 1, v5
	v_lshlrev_b64 v[50:51], 11, v[48:49]
	v_add3_u32 v49, s88, v3, v6
	v_lshl_or_b32 v3, s20, 6, v220
	v_or_b32_e32 v52, 8, v42
	v_cmp_lt_u32_e64 s[42:43], v9, v7
	v_sub_u32_e32 v9, 2, v5
	s_lshl_b32 s30, s82, 10
	v_lshlrev_b32_e32 v57, 3, v3
	v_lshlrev_b32_e32 v59, 5, v3
	v_lshrrev_b32_e32 v3, 1, v48
	v_lshrrev_b32_e32 v10, 1, v52
	v_cmp_lt_u32_e64 s[44:45], v9, v7
	v_sub_u32_e32 v9, 3, v5
	s_add_i32 s84, 0, 0x20000
	v_lshl_add_u32 v194, v245, 2, s84
	v_add_u32_e32 v195, -4, v194
	v_add_u32_e32 v196, -8, v194
	v_add_u32_e32 v197, -12, v194
	v_add_u32_e32 v198, -16, v194
	v_add_u32_e32 v199, -20, v194
	v_add_u32_e32 v200, -24, v194
	v_add_u32_e32 v201, -28, v194
	s_and_b32 s85, s82, -4
	s_add_i32 s86, s30, 0
	s_and_b32 s87, s82, 4
	v_xor_b32_e32 v3, v3, v218
	v_xor_b32_e32 v6, v39, v220
	v_xor_b32_e32 v10, v10, v220
	v_cmp_lt_u32_e64 s[46:47], v9, v7
	v_sub_u32_e32 v9, 4, v5
	s_cmp_eq_u32 s85, 4
	v_bitop3_b32 v4, v4, v43, 4 bitop3:0x6c
	v_lshlrev_b32_e32 v6, 3, v6
	v_lshlrev_b32_e32 v10, 3, v10
	v_cmp_lt_u32_e64 s[48:49], v9, v7
	v_sub_u32_e32 v9, 5, v5
	v_lshlrev_b32_e32 v3, 4, v3
	v_readlane_b32 s13, v163, 40
	v_lshlrev_b32_e32 v2, 3, v2
	s_cselect_b64 s[36:37], -1, 0
	s_cmp_lt_u32 s82, 4
	v_lshlrev_b32_e32 v4, 3, v4
	v_and_b32_e32 v6, 56, v6
	v_lshlrev_b32_e32 v8, 3, v8
	v_and_b32_e32 v10, 56, v10
	v_lshlrev_b32_e32 v12, 3, v12
	v_cmp_lt_u32_e64 s[50:51], v9, v7
	v_sub_u32_e32 v9, 6, v5
	v_sub_u32_e32 v5, 7, v5
	v_and_b32_e32 v22, 0x70, v3
	v_mov_b32_e32 v23, v1
	v_lshl_add_u32 v53, v218, 2, s84
	s_cselect_b64 s[12:13], -1, 0
	s_cbranch_scc1 .Latt_noprio
	s_setprio 1
